# mix-out EpiResid hand-written: second-half x loads issued row by row ahead of first-half stores, counted vmcnt
# baseline (speedup 1.0000x reference)
; #define PG8_STAGE(bufoff, gbase, voff) do { _Pragma("unroll") for (int _i = 0; _i < 2; ++_i) \
;         __builtin_amdgcn_global_load_lds((const unsigned*)((const char*)(gbase) + (voff)[_i]), (LAS unsigned*)(lds + (bufoff) + ldsw + _i * 8192), 16, 0, 0); } while (0)
; #define PG8_LDA(dst, b, h) do { _Pragma("unroll") for (int m = 0; m < 4; ++m) _Pragma("unroll") for (int k = 0; k < 2; ++k) dst[m][k] = *(const LAS bf16x8*)(lds + PG8_SA(b, h) + aoff + m * 2048 + k * 1024); } while (0)
; #define PG8_LDB(dst, b, h) do { _Pragma("unroll") for (int n = 0; n < 2; ++n) _Pragma("unroll") for (int k = 0; k < 2; ++k) dst[n][k] = *(const LAS bf16x8*)(lds + PG8_SB(b, h) + boff + n * 2048 + k * 1024); } while (0)
; #define PG8_MMA(ai, bj, At, Bt) do { __builtin_amdgcn_s_setprio(1); _Pragma("unroll") for (int m = 0; m < 4; ++m) _Pragma("unroll") for (int n = 0; n < 2; ++n) _Pragma("unroll") for (int k = 0; k < 2; ++k) \
;         acc[ai][bj][m][n] = __builtin_amdgcn_mfma_f32_16x16x32_bf16(Bt[n][k], At[m][k], acc[ai][bj][m][n], 0, 0, 0); __builtin_amdgcn_s_setprio(0); } while (0)
; #define PG8_WAIT_L(n) asm volatile("s_waitcnt lgkmcnt(" #n ")" ::: "memory")
; #define PG8_BAR __builtin_amdgcn_s_barrier()
; #define PG8_SCHED __builtin_amdgcn_sched_barrier(0)
; template <class Epi, class Sched>
; DI void gemm_phase(LAS unsigned char* lds, const Gemm g, const Sched& S, const Epi& E) {
;     ...
;             PG8_LDB(B0, 1, 0); PG8_SCHED; PG8_LDA(At, 1, 0); PG8_STAGE(PG8_SA(0, 1), a2 + hstep, voffA);
;             PG8_WAIT_L(8); PG8_BAR; PG8_WAIT_L(0); PG8_MMA(0, 0, At, B0); PG8_BAR; PG8_SCHED;
;             PG8_LDB(B1, 1, 1); PG8_STAGE(PG8_SB(1, 0), b3, voffB);
;             PG8_BAR; PG8_WAIT_L(0); PG8_MMA(0, 1, At, B1); PG8_BAR;
;             PG8_LDA(At, 1, 1); PG8_STAGE(PG8_SA(1, 0), a3, voffA);
;             PG8_BAR; PG8_WAIT_L(0); PG8_MMA(1, 0, At, B0); PG8_BAR; PG8_SCHED;
.Lkmid_22849:
	s_add_i32 s42, 0, 0x18000
	v_add_u32_e32 v142, s42, v198
	s_barrier
	ds_read_b128 v[130:133], v142
	ds_read_b128 v[134:137], v142 offset:1024
	ds_read_b128 v[138:141], v142 offset:2048
	ds_read_b128 v[142:145], v142 offset:3072
	s_add_u32 s0, s22, 0x40000
	s_addc_u32 s1, s23, 0
	s_mov_b32 m0, s24
	v_lshl_add_u64 v[184:185], s[0:1], 0, v[96:97]
	ds_read_b128 v[146:149], v200 offset:32768
	ds_read_b128 v[150:153], v200 offset:33792
	ds_read_b128 v[154:157], v200 offset:34816
	ds_read_b128 v[158:161], v200 offset:35840
	ds_read_b128 v[162:165], v200 offset:36864
	ds_read_b128 v[166:169], v200 offset:37888
	ds_read_b128 v[170:173], v200 offset:38912
	ds_read_b128 v[174:177], v200 offset:39936
	global_load_lds_dwordx4 v[184:185], off
	v_lshl_add_u64 v[184:185], s[0:1], 0, v[178:179]
	s_mov_b32 m0, s25
	s_nop 0
	global_load_lds_dwordx4 v[184:185], off
	s_waitcnt lgkmcnt(8)
	s_barrier
	s_waitcnt lgkmcnt(0)
	s_setprio 1
	s_waitcnt lgkmcnt(0)
	v_mfma_f32_16x16x32_bf16 v[126:129], v[130:133], v[146:149], v[126:129]
	v_mfma_f32_16x16x32_bf16 v[122:125], v[138:141], v[146:149], v[122:125]
	v_mfma_f32_16x16x32_bf16 v[110:113], v[130:133], v[154:157], v[110:113]
	v_mfma_f32_16x16x32_bf16 v[106:109], v[138:141], v[154:157], v[106:109]
	v_mfma_f32_16x16x32_bf16 v[92:95], v[130:133], v[162:165], v[92:95]
	v_mfma_f32_16x16x32_bf16 v[88:91], v[138:141], v[162:165], v[88:91]
	v_mfma_f32_16x16x32_bf16 v[76:79], v[130:133], v[170:173], v[76:79]
	v_mfma_f32_16x16x32_bf16 v[72:75], v[138:141], v[170:173], v[72:75]
	v_mfma_f32_16x16x32_bf16 v[126:129], v[134:137], v[150:153], v[126:129]
	v_mfma_f32_16x16x32_bf16 v[122:125], v[142:145], v[150:153], v[122:125]
	v_mfma_f32_16x16x32_bf16 v[110:113], v[134:137], v[158:161], v[110:113]
	v_mfma_f32_16x16x32_bf16 v[106:109], v[142:145], v[158:161], v[106:109]
	v_mfma_f32_16x16x32_bf16 v[92:95], v[134:137], v[166:169], v[92:95]
	v_mfma_f32_16x16x32_bf16 v[88:91], v[142:145], v[166:169], v[88:91]
	v_mfma_f32_16x16x32_bf16 v[76:79], v[134:137], v[174:177], v[76:79]
	v_mfma_f32_16x16x32_bf16 v[72:75], v[142:145], v[174:177], v[72:75]
	s_setprio 0
	s_barrier
	s_add_i32 s22, 0, 0x1c000
	s_add_i32 s0, s42, s5
	v_add_u32_e32 v196, s22, v198
	v_lshl_add_u64 v[206:207], v[206:207], 0, s[36:37]
	s_mov_b32 m0, s0
	ds_read_b128 v[184:187], v196
	ds_read_b128 v[188:191], v196 offset:1024
	ds_read_b128 v[192:195], v196 offset:2048
	ds_read_b128 v[202:205], v196 offset:3072
	global_load_lds_dwordx4 v[206:207], off
	v_lshl_add_u64 v[206:207], v[208:209], 0, s[36:37]
	s_add_i32 m0, s0, 0x2000
	s_nop 0
	global_load_lds_dwordx4 v[206:207], off
	s_barrier
	s_waitcnt lgkmcnt(0)
	s_setprio 1
	s_waitcnt lgkmcnt(0)
	v_mfma_f32_16x16x32_bf16 v[118:121], v[184:187], v[146:149], v[118:121]
	v_mfma_f32_16x16x32_bf16 v[114:117], v[192:195], v[146:149], v[114:117]
	v_mfma_f32_16x16x32_bf16 v[102:105], v[184:187], v[154:157], v[102:105]
	v_mfma_f32_16x16x32_bf16 v[98:101], v[192:195], v[154:157], v[98:101]
	v_mfma_f32_16x16x32_bf16 v[84:87], v[184:187], v[162:165], v[84:87]
	v_mfma_f32_16x16x32_bf16 v[80:83], v[192:195], v[162:165], v[80:83]
	v_mfma_f32_16x16x32_bf16 v[68:71], v[184:187], v[170:173], v[68:71]
	v_mfma_f32_16x16x32_bf16 v[64:67], v[192:195], v[170:173], v[64:67]
	v_mfma_f32_16x16x32_bf16 v[118:121], v[188:191], v[150:153], v[118:121]
	v_mfma_f32_16x16x32_bf16 v[114:117], v[202:205], v[150:153], v[114:117]
	v_mfma_f32_16x16x32_bf16 v[102:105], v[188:191], v[158:161], v[102:105]
	v_mfma_f32_16x16x32_bf16 v[98:101], v[202:205], v[158:161], v[98:101]
	v_mfma_f32_16x16x32_bf16 v[84:87], v[188:191], v[166:169], v[84:87]
	v_mfma_f32_16x16x32_bf16 v[80:83], v[202:205], v[166:169], v[80:83]
	v_mfma_f32_16x16x32_bf16 v[68:71], v[188:191], v[174:177], v[68:71]
	v_mfma_f32_16x16x32_bf16 v[64:67], v[202:205], v[174:177], v[64:67]
	s_setprio 0
	s_mov_b32 m0, s27
	v_lshl_add_u64 v[206:207], v[210:211], 0, s[36:37]
	s_barrier
	ds_read_b128 v[146:149], v200 offset:49152
	ds_read_b128 v[150:153], v200 offset:50176
	ds_read_b128 v[154:157], v200 offset:51200
	ds_read_b128 v[158:161], v200 offset:52224
	ds_read_b128 v[162:165], v200 offset:53248
	ds_read_b128 v[166:169], v200 offset:54272
	ds_read_b128 v[170:173], v200 offset:55296
	ds_read_b128 v[174:177], v200 offset:56320
	global_load_lds_dwordx4 v[206:207], off
	v_lshl_add_u64 v[206:207], v[212:213], 0, s[36:37]
	s_mov_b32 m0, s28
	s_nop 0
	global_load_lds_dwordx4 v[206:207], off
	s_barrier
	s_waitcnt lgkmcnt(0)
	s_setprio 1
	s_waitcnt lgkmcnt(0)
	v_mfma_f32_16x16x32_bf16 v[60:63], v[130:133], v[146:149], v[60:63]
	v_mfma_f32_16x16x32_bf16 v[56:59], v[138:141], v[146:149], v[56:59]
	v_mfma_f32_16x16x32_bf16 v[44:47], v[130:133], v[154:157], v[44:47]
	v_mfma_f32_16x16x32_bf16 v[40:43], v[138:141], v[154:157], v[40:43]
	v_mfma_f32_16x16x32_bf16 v[28:31], v[130:133], v[162:165], v[28:31]
	v_mfma_f32_16x16x32_bf16 v[24:27], v[138:141], v[162:165], v[24:27]
	v_mfma_f32_16x16x32_bf16 v[12:15], v[130:133], v[170:173], v[12:15]
	v_mfma_f32_16x16x32_bf16 v[8:11], v[138:141], v[170:173], v[8:11]
	v_mfma_f32_16x16x32_bf16 v[60:63], v[134:137], v[150:153], v[60:63]
	v_mfma_f32_16x16x32_bf16 v[56:59], v[142:145], v[150:153], v[56:59]
	v_mfma_f32_16x16x32_bf16 v[44:47], v[134:137], v[158:161], v[44:47]
	v_mfma_f32_16x16x32_bf16 v[40:43], v[142:145], v[158:161], v[40:43]
	v_mfma_f32_16x16x32_bf16 v[28:31], v[134:137], v[166:169], v[28:31]
	v_mfma_f32_16x16x32_bf16 v[24:27], v[142:145], v[166:169], v[24:27]
	v_mfma_f32_16x16x32_bf16 v[12:15], v[134:137], v[174:177], v[12:15]
	v_mfma_f32_16x16x32_bf16 v[8:11], v[142:145], v[174:177], v[8:11]
	s_setprio 0
	s_barrier
; #define LAS __attribute__((address_space(3)))
; DI unsigned pk2(float lo, float hi) { f32x2 v = {lo, hi}; hbf2 r = __builtin_convertvector(v, hbf2); return __builtin_bit_cast(unsigned, r); }
; #define PG8_WAIT_V(n) asm volatile("s_waitcnt vmcnt(" #n ")" ::: "memory")
; #define PG8_BAR __builtin_amdgcn_s_barrier()
; template <class Epi, class Sched>
; DI void gemm_phase(LAS unsigned char* lds, const Gemm g, const Sched& S, const Epi& E) {
;     ...
;             PG8_STAGE(PG8_SB(1, 1), b3 + hstep, voffB);
;             PG8_WAIT_V(6); PG8_BAR; PG8_MMA(1, 1, At, B1); PG8_BAR;
;     DI void operator()(f32x4 (&acc)[2][2][4][2], const Unit& u, int wr, int wc, int fr, int fq, LAS unsigned char* lds) const {
;         const int row0 = u.pm * 256 + wr * 64 + fr, col0 = u.pn * 256 + wc * 32 + 4 * fq;
; #pragma unroll
;         for (int ai = 0; ai < 2; ++ai) {
;             f32x4 xv[4][2][2];
; #pragma unroll
;             for (int m = 0; m < 4; ++m) {
;                 const int row = row0 + ai * 128 + m * 16;
;                 const float* xi = (row < TP ? xin_p + (size_t)row * DM : xin_s + (size_t)(row - TP) * DM) + col0;
; #pragma unroll
;                 for (int bj = 0; bj < 2; ++bj)
; #pragma unroll
;                     for (int n = 0; n < 2; ++n) xv[m][bj][n] = *(const f32x4*)(xi + bj * 128 + n * 16);
;             }
; #pragma unroll
;             for (int m = 0; m < 4; ++m) {
;                 const int row = row0 + ai * 128 + m * 16;
;                 float* xo = X + (size_t)row * DM + col0; bf16_t* xb = XB + (size_t)row * DM + col0;
;                 float ssq = 0.f;
; #pragma unroll
;                 for (int bj = 0; bj < 2; ++bj)
; #pragma unroll
;                     for (int n = 0; n < 2; ++n) {
;                         const int c = bj * 128 + n * 16;
;                         const f32x4 o = xv[m][bj][n] + acc[ai][bj][m][n] * scale;
;                         *(f32x4*)(xo + c) = o;
;                         if (wxb) { u32x2 w; w.x = pk2(o[0], o[1]); w.y = pk2(o[2], o[3]); *(u32x2*)(xb + c) = w; }
;                         ssq += (o[0] * o[0] + o[1] * o[1]) + (o[2] * o[2] + o[3] * o[3]);
;                     }
;                 ssq += __shfl_xor(ssq, 16); ssq += __shfl_xor(ssq, 32);
;                 if (fq == 0) SS[(size_t)row * 16 + u.pn * 4 + wc] = ssq;
;             }
	s_add_u32 s0, s20, 0x40080
	s_addc_u32 s1, s21, 0
	s_add_i32 s20, s22, s5
	v_lshl_add_u64 v[130:131], s[0:1], 0, v[96:97]
	s_mov_b32 m0, s20
	s_nop 0
	global_load_lds_dwordx4 v[130:131], off
	v_lshl_add_u64 v[130:131], s[0:1], 0, v[178:179]
	s_add_i32 m0, s20, 0x2000
	s_nop 0
	global_load_lds_dwordx4 v[130:131], off
	s_waitcnt vmcnt(6)
	s_barrier
	s_setprio 1
	v_mfma_f32_16x16x32_bf16 v[52:55], v[184:187], v[146:149], v[52:55]
	v_mfma_f32_16x16x32_bf16 v[48:51], v[192:195], v[146:149], v[48:51]
	v_mfma_f32_16x16x32_bf16 v[36:39], v[184:187], v[154:157], v[36:39]
	v_mfma_f32_16x16x32_bf16 v[32:35], v[192:195], v[154:157], v[32:35]
	v_mfma_f32_16x16x32_bf16 v[20:23], v[184:187], v[162:165], v[20:23]
	v_mfma_f32_16x16x32_bf16 v[16:19], v[192:195], v[162:165], v[16:19]
	v_mfma_f32_16x16x32_bf16 v[4:7], v[184:187], v[170:173], v[4:7]
	v_mfma_f32_16x16x32_bf16 v[0:3], v[192:195], v[170:173], v[0:3]
	v_mfma_f32_16x16x32_bf16 v[52:55], v[188:191], v[150:153], v[52:55]
	v_mfma_f32_16x16x32_bf16 v[48:51], v[202:205], v[150:153], v[48:51]
	v_mfma_f32_16x16x32_bf16 v[36:39], v[188:191], v[158:161], v[36:39]
	v_mfma_f32_16x16x32_bf16 v[32:35], v[202:205], v[158:161], v[32:35]
	v_mfma_f32_16x16x32_bf16 v[20:23], v[188:191], v[166:169], v[20:23]
	v_mfma_f32_16x16x32_bf16 v[16:19], v[202:205], v[166:169], v[16:19]
	v_mfma_f32_16x16x32_bf16 v[4:7], v[188:191], v[174:177], v[4:7]
	v_mfma_f32_16x16x32_bf16 v[0:3], v[202:205], v[174:177], v[0:3]
	s_setprio 0
	s_add_i32 s41, s41, 2
	s_add_u32 s18, s18, 0x100
	s_addc_u32 s19, s19, 0
	s_add_u32 s34, s34, 0x100
	s_addc_u32 s40, s40, 0
	s_cmp_lt_u32 s41, 14
	s_barrier
	s_cbranch_scc1 .LBB0_1684
	v_lshl_add_u32 v186, s2, 8, v197
	v_lshl_or_b32 v184, s30, 8, v199
	v_lshlrev_b32_e32 v187, 12, v186
	v_lshl_add_u32 v187, v184, 2, v187
	v_lshrrev_b32_e32 v188, 1, v187
	s_lshl_b32 s0, s30, 2
	s_add_i32 s0, s0, s26
	s_lshl_b32 s0, s0, 2
	v_lshl_add_u32 v189, v186, 6, s0
	v_xor_b32_e32 v193, 16, v229
	v_lshlrev_b32_e32 v193, 2, v193
	v_xor_b32_e32 v201, 32, v229
	v_lshlrev_b32_e32 v201, 2, v201
	s_mov_b32 s34, s57
	v_add_u32_e32 v190, 0x0, v187
	global_load_dwordx4 v[130:133], v190, s[90:91]
	global_load_dwordx4 v[134:137], v190, s[90:91] offset:64
	global_load_dwordx4 v[138:141], v190, s[90:91] offset:512
	global_load_dwordx4 v[142:145], v190, s[90:91] offset:576
	v_add_u32_e32 v190, 0x10000, v187
	global_load_dwordx4 v[146:149], v190, s[90:91]
	global_load_dwordx4 v[150:153], v190, s[90:91] offset:64
	global_load_dwordx4 v[154:157], v190, s[90:91] offset:512
	global_load_dwordx4 v[158:161], v190, s[90:91] offset:576
	v_add_u32_e32 v190, 0x20000, v187
	global_load_dwordx4 v[162:165], v190, s[90:91]
	global_load_dwordx4 v[166:169], v190, s[90:91] offset:64
	global_load_dwordx4 v[170:173], v190, s[90:91] offset:512
	global_load_dwordx4 v[174:177], v190, s[90:91] offset:576
	v_add_u32_e32 v190, 0x30000, v187
	global_load_dwordx4 v[204:207], v190, s[90:91]
	global_load_dwordx4 v[208:211], v190, s[90:91] offset:64
	global_load_dwordx4 v[212:215], v190, s[90:91] offset:512
	global_load_dwordx4 v[216:219], v190, s[90:91] offset:576
	s_waitcnt vmcnt(0)
	v_pk_add_f32 v[128:129], v[128:129], v[132:133]
	v_pk_add_f32 v[126:127], v[126:127], v[130:131]
	v_pk_add_f32 v[124:125], v[124:125], v[136:137]
	v_pk_add_f32 v[122:123], v[122:123], v[134:135]
	v_pk_add_f32 v[120:121], v[120:121], v[140:141]
	v_pk_add_f32 v[118:119], v[118:119], v[138:139]
	v_pk_add_f32 v[116:117], v[116:117], v[144:145]
	v_pk_add_f32 v[114:115], v[114:115], v[142:143]
	v_add_u32_e32 v190, 0x80000, v187
	global_load_dwordx4 v[130:133], v190, s[90:91]
	global_load_dwordx4 v[134:137], v190, s[90:91] offset:64
	global_load_dwordx4 v[138:141], v190, s[90:91] offset:512
	global_load_dwordx4 v[142:145], v190, s[90:91] offset:576
	v_add_u32_e32 v191, 0x0, v187
	v_add_u32_e32 v192, 0x0, v188
	global_store_dwordx4 v191, v[126:129], s[90:91]
	v_cvt_pk_bf16_f32 v194, v126, v127
	v_cvt_pk_bf16_f32 v195, v128, v129
	global_store_dwordx2 v192, v[194:195], s[72:73]
	v_mul_f32_e32 v185, v127, v127
	v_fmac_f32_e32 v185, v126, v126
	v_mul_f32_e32 v196, v129, v129
	v_fmac_f32_e32 v196, v128, v128
	v_add_f32_e32 v220, v185, v196
	global_store_dwordx4 v191, v[122:125], s[90:91] offset:64
	v_cvt_pk_bf16_f32 v202, v122, v123
	v_cvt_pk_bf16_f32 v203, v124, v125
	global_store_dwordx2 v192, v[202:203], s[72:73] offset:32
	v_mul_f32_e32 v185, v123, v123
	v_fmac_f32_e32 v185, v122, v122
	v_mul_f32_e32 v196, v125, v125
	v_fmac_f32_e32 v196, v124, v124
	v_add_f32_e32 v185, v185, v196
	v_add_f32_e32 v220, v220, v185
	global_store_dwordx4 v191, v[118:121], s[90:91] offset:512
	v_cvt_pk_bf16_f32 v194, v118, v119
	v_cvt_pk_bf16_f32 v195, v120, v121
	global_store_dwordx2 v192, v[194:195], s[72:73] offset:256
	v_mul_f32_e32 v185, v119, v119
	v_fmac_f32_e32 v185, v118, v118
	v_mul_f32_e32 v196, v121, v121
	v_fmac_f32_e32 v196, v120, v120
	v_add_f32_e32 v185, v185, v196
	v_add_f32_e32 v220, v220, v185
	global_store_dwordx4 v191, v[114:117], s[90:91] offset:576
	v_cvt_pk_bf16_f32 v202, v114, v115
	v_cvt_pk_bf16_f32 v203, v116, v117
	global_store_dwordx2 v192, v[202:203], s[72:73] offset:288
	v_mul_f32_e32 v185, v115, v115
	v_fmac_f32_e32 v185, v114, v114
	v_mul_f32_e32 v196, v117, v117
	v_fmac_f32_e32 v196, v116, v116
	v_add_f32_e32 v185, v185, v196
	v_add_f32_e32 v220, v220, v185
	v_pk_add_f32 v[112:113], v[112:113], v[148:149]
	v_pk_add_f32 v[110:111], v[110:111], v[146:147]
	v_pk_add_f32 v[108:109], v[108:109], v[152:153]
	v_pk_add_f32 v[106:107], v[106:107], v[150:151]
	v_pk_add_f32 v[104:105], v[104:105], v[156:157]
	v_pk_add_f32 v[102:103], v[102:103], v[154:155]
	v_pk_add_f32 v[100:101], v[100:101], v[160:161]
; DI unsigned pk2(float lo, float hi) { f32x2 v = {lo, hi}; hbf2 r = __builtin_convertvector(v, hbf2); return __builtin_bit_cast(unsigned, r); }
;     DI void operator()(f32x4 (&acc)[2][2][4][2], const Unit& u, int wr, int wc, int fr, int fq, LAS unsigned char* lds) const {
;     ...
; #pragma unroll
;             for (int m = 0; m < 4; ++m) {
;                 const int row = row0 + ai * 128 + m * 16;
;                 float* xo = X + (size_t)row * DM + col0; bf16_t* xb = XB + (size_t)row * DM + col0;
;                 float ssq = 0.f;
; #pragma unroll
;                 for (int bj = 0; bj < 2; ++bj)
; #pragma unroll
;                     for (int n = 0; n < 2; ++n) {
;                         const int c = bj * 128 + n * 16;
;                         const f32x4 o = xv[m][bj][n] + acc[ai][bj][m][n] * scale;
;                         *(f32x4*)(xo + c) = o;
;                         if (wxb) { u32x2 w; w.x = pk2(o[0], o[1]); w.y = pk2(o[2], o[3]); *(u32x2*)(xb + c) = w; }
;                         ssq += (o[0] * o[0] + o[1] * o[1]) + (o[2] * o[2] + o[3] * o[3]);
;                     }
;                 ssq += __shfl_xor(ssq, 16); ssq += __shfl_xor(ssq, 32);
;                 if (fq == 0) SS[(size_t)row * 16 + u.pn * 4 + wc] = ssq;
;             }
	v_pk_add_f32 v[98:99], v[98:99], v[158:159]
	v_add_u32_e32 v190, 0x90000, v187
	global_load_dwordx4 v[146:149], v190, s[90:91]
	global_load_dwordx4 v[150:153], v190, s[90:91] offset:64
	global_load_dwordx4 v[154:157], v190, s[90:91] offset:512
	global_load_dwordx4 v[158:161], v190, s[90:91] offset:576
	v_add_u32_e32 v191, 0x10000, v187
	v_add_u32_e32 v192, 0x8000, v188
	global_store_dwordx4 v191, v[110:113], s[90:91]
	v_cvt_pk_bf16_f32 v194, v110, v111
	v_cvt_pk_bf16_f32 v195, v112, v113
	global_store_dwordx2 v192, v[194:195], s[72:73]
	v_mul_f32_e32 v185, v111, v111
	v_fmac_f32_e32 v185, v110, v110
	v_mul_f32_e32 v196, v113, v113
	v_fmac_f32_e32 v196, v112, v112
	v_add_f32_e32 v221, v185, v196
	global_store_dwordx4 v191, v[106:109], s[90:91] offset:64
	v_cvt_pk_bf16_f32 v202, v106, v107
	v_cvt_pk_bf16_f32 v203, v108, v109
	global_store_dwordx2 v192, v[202:203], s[72:73] offset:32
	v_mul_f32_e32 v185, v107, v107
	v_fmac_f32_e32 v185, v106, v106
	v_mul_f32_e32 v196, v109, v109
	v_fmac_f32_e32 v196, v108, v108
	v_add_f32_e32 v185, v185, v196
	v_add_f32_e32 v221, v221, v185
	global_store_dwordx4 v191, v[102:105], s[90:91] offset:512
	v_cvt_pk_bf16_f32 v194, v102, v103
	v_cvt_pk_bf16_f32 v195, v104, v105
	global_store_dwordx2 v192, v[194:195], s[72:73] offset:256
	v_mul_f32_e32 v185, v103, v103
	v_fmac_f32_e32 v185, v102, v102
	v_mul_f32_e32 v196, v105, v105
	v_fmac_f32_e32 v196, v104, v104
	v_add_f32_e32 v185, v185, v196
	v_add_f32_e32 v221, v221, v185
	global_store_dwordx4 v191, v[98:101], s[90:91] offset:576
	v_cvt_pk_bf16_f32 v202, v98, v99
	v_cvt_pk_bf16_f32 v203, v100, v101
	global_store_dwordx2 v192, v[202:203], s[72:73] offset:288
	v_mul_f32_e32 v185, v99, v99
	v_fmac_f32_e32 v185, v98, v98
	v_mul_f32_e32 v196, v101, v101
	v_fmac_f32_e32 v196, v100, v100
	v_add_f32_e32 v185, v185, v196
	v_add_f32_e32 v221, v221, v185
	v_pk_add_f32 v[94:95], v[94:95], v[164:165]
	v_pk_add_f32 v[92:93], v[92:93], v[162:163]
	v_pk_add_f32 v[90:91], v[90:91], v[168:169]
	v_pk_add_f32 v[88:89], v[88:89], v[166:167]
	v_pk_add_f32 v[86:87], v[86:87], v[172:173]
	v_pk_add_f32 v[84:85], v[84:85], v[170:171]
	v_pk_add_f32 v[82:83], v[82:83], v[176:177]
	v_pk_add_f32 v[80:81], v[80:81], v[174:175]
	v_add_u32_e32 v190, 0xa0000, v187
	global_load_dwordx4 v[162:165], v190, s[90:91]
	global_load_dwordx4 v[166:169], v190, s[90:91] offset:64
	global_load_dwordx4 v[170:173], v190, s[90:91] offset:512
	global_load_dwordx4 v[174:177], v190, s[90:91] offset:576
	v_add_u32_e32 v191, 0x20000, v187
	v_add_u32_e32 v192, 0x10000, v188
	global_store_dwordx4 v191, v[92:95], s[90:91]
	v_cvt_pk_bf16_f32 v194, v92, v93
	v_cvt_pk_bf16_f32 v195, v94, v95
	global_store_dwordx2 v192, v[194:195], s[72:73]
	v_mul_f32_e32 v185, v93, v93
	v_fmac_f32_e32 v185, v92, v92
	v_mul_f32_e32 v196, v95, v95
	v_fmac_f32_e32 v196, v94, v94
	v_add_f32_e32 v222, v185, v196
	global_store_dwordx4 v191, v[88:91], s[90:91] offset:64
	v_cvt_pk_bf16_f32 v202, v88, v89
	v_cvt_pk_bf16_f32 v203, v90, v91
	global_store_dwordx2 v192, v[202:203], s[72:73] offset:32
	v_mul_f32_e32 v185, v89, v89
	v_fmac_f32_e32 v185, v88, v88
	v_mul_f32_e32 v196, v91, v91
	v_fmac_f32_e32 v196, v90, v90
	v_add_f32_e32 v185, v185, v196
	v_add_f32_e32 v222, v222, v185
	global_store_dwordx4 v191, v[84:87], s[90:91] offset:512
	v_cvt_pk_bf16_f32 v194, v84, v85
	v_cvt_pk_bf16_f32 v195, v86, v87
	global_store_dwordx2 v192, v[194:195], s[72:73] offset:256
	v_mul_f32_e32 v185, v85, v85
	v_fmac_f32_e32 v185, v84, v84
	v_mul_f32_e32 v196, v87, v87
	v_fmac_f32_e32 v196, v86, v86
	v_add_f32_e32 v185, v185, v196
	v_add_f32_e32 v222, v222, v185
	global_store_dwordx4 v191, v[80:83], s[90:91] offset:576
	v_cvt_pk_bf16_f32 v202, v80, v81
	v_cvt_pk_bf16_f32 v203, v82, v83
	global_store_dwordx2 v192, v[202:203], s[72:73] offset:288
	v_mul_f32_e32 v185, v81, v81
	v_fmac_f32_e32 v185, v80, v80
	v_mul_f32_e32 v196, v83, v83
	v_fmac_f32_e32 v196, v82, v82
	v_add_f32_e32 v185, v185, v196
	v_add_f32_e32 v222, v222, v185
	v_pk_add_f32 v[78:79], v[78:79], v[206:207]
	v_pk_add_f32 v[76:77], v[76:77], v[204:205]
	v_pk_add_f32 v[74:75], v[74:75], v[210:211]
	v_pk_add_f32 v[72:73], v[72:73], v[208:209]
	v_pk_add_f32 v[70:71], v[70:71], v[214:215]
	v_pk_add_f32 v[68:69], v[68:69], v[212:213]
	v_pk_add_f32 v[66:67], v[66:67], v[218:219]
	v_pk_add_f32 v[64:65], v[64:65], v[216:217]
	v_add_u32_e32 v190, 0xb0000, v187
	global_load_dwordx4 v[204:207], v190, s[90:91]
	global_load_dwordx4 v[208:211], v190, s[90:91] offset:64
	global_load_dwordx4 v[212:215], v190, s[90:91] offset:512
	global_load_dwordx4 v[216:219], v190, s[90:91] offset:576
	v_add_u32_e32 v191, 0x30000, v187
	v_add_u32_e32 v192, 0x18000, v188
	global_store_dwordx4 v191, v[76:79], s[90:91]
	v_cvt_pk_bf16_f32 v194, v76, v77
	v_cvt_pk_bf16_f32 v195, v78, v79
	global_store_dwordx2 v192, v[194:195], s[72:73]
	v_mul_f32_e32 v185, v77, v77
	v_fmac_f32_e32 v185, v76, v76
	v_mul_f32_e32 v196, v79, v79
	v_fmac_f32_e32 v196, v78, v78
	v_add_f32_e32 v223, v185, v196
	global_store_dwordx4 v191, v[72:75], s[90:91] offset:64
	v_cvt_pk_bf16_f32 v202, v72, v73
	v_cvt_pk_bf16_f32 v203, v74, v75
	global_store_dwordx2 v192, v[202:203], s[72:73] offset:32
	v_mul_f32_e32 v185, v73, v73
	v_fmac_f32_e32 v185, v72, v72
	v_mul_f32_e32 v196, v75, v75
	v_fmac_f32_e32 v196, v74, v74
	v_add_f32_e32 v185, v185, v196
	v_add_f32_e32 v223, v223, v185
	global_store_dwordx4 v191, v[68:71], s[90:91] offset:512
	v_cvt_pk_bf16_f32 v194, v68, v69
	v_cvt_pk_bf16_f32 v195, v70, v71
	global_store_dwordx2 v192, v[194:195], s[72:73] offset:256
	v_mul_f32_e32 v185, v69, v69
	v_fmac_f32_e32 v185, v68, v68
	v_mul_f32_e32 v196, v71, v71
	v_fmac_f32_e32 v196, v70, v70
	v_add_f32_e32 v185, v185, v196
	v_add_f32_e32 v223, v223, v185
	global_store_dwordx4 v191, v[64:67], s[90:91] offset:576
	v_cvt_pk_bf16_f32 v202, v64, v65
	v_cvt_pk_bf16_f32 v203, v66, v67
	global_store_dwordx2 v192, v[202:203], s[72:73] offset:288
	v_mul_f32_e32 v185, v65, v65
	v_fmac_f32_e32 v185, v64, v64
	v_mul_f32_e32 v196, v67, v67
	v_fmac_f32_e32 v196, v66, v66
	v_add_f32_e32 v185, v185, v196
	v_add_f32_e32 v223, v223, v185
	ds_bpermute_b32 v224, v193, v220
	ds_bpermute_b32 v225, v193, v221
	ds_bpermute_b32 v226, v193, v222
	ds_bpermute_b32 v227, v193, v223
	s_waitcnt lgkmcnt(0)
; DI unsigned pk2(float lo, float hi) { f32x2 v = {lo, hi}; hbf2 r = __builtin_convertvector(v, hbf2); return __builtin_bit_cast(unsigned, r); }
;     DI void operator()(f32x4 (&acc)[2][2][4][2], const Unit& u, int wr, int wc, int fr, int fq, LAS unsigned char* lds) const {
;     ...
; #pragma unroll
;             for (int m = 0; m < 4; ++m) {
;                 const int row = row0 + ai * 128 + m * 16;
;                 float* xo = X + (size_t)row * DM + col0; bf16_t* xb = XB + (size_t)row * DM + col0;
;                 float ssq = 0.f;
; #pragma unroll
;                 for (int bj = 0; bj < 2; ++bj)
; #pragma unroll
;                     for (int n = 0; n < 2; ++n) {
;                         const int c = bj * 128 + n * 16;
;                         const f32x4 o = xv[m][bj][n] + acc[ai][bj][m][n] * scale;
;                         *(f32x4*)(xo + c) = o;
;                         if (wxb) { u32x2 w; w.x = pk2(o[0], o[1]); w.y = pk2(o[2], o[3]); *(u32x2*)(xb + c) = w; }
;                         ssq += (o[0] * o[0] + o[1] * o[1]) + (o[2] * o[2] + o[3] * o[3]);
;                     }
;                 ssq += __shfl_xor(ssq, 16); ssq += __shfl_xor(ssq, 32);
;                 if (fq == 0) SS[(size_t)row * 16 + u.pn * 4 + wc] = ssq;
;             }
	v_add_f32_e32 v220, v220, v224
	v_add_f32_e32 v221, v221, v225
	v_add_f32_e32 v222, v222, v226
	v_add_f32_e32 v223, v223, v227
	ds_bpermute_b32 v224, v201, v220
	ds_bpermute_b32 v225, v201, v221
	ds_bpermute_b32 v226, v201, v222
	ds_bpermute_b32 v227, v201, v223
	s_waitcnt lgkmcnt(0)
	v_add_f32_e32 v220, v220, v224
	v_add_f32_e32 v221, v221, v225
	v_add_f32_e32 v222, v222, v226
	v_add_f32_e32 v223, v223, v227
	s_and_saveexec_b64 s[18:19], s[38:39]
	v_add_u32_e32 v190, 0x0, v189
	global_store_dword v190, v220, s[70:71]
	v_add_u32_e32 v190, 0x400, v189
	global_store_dword v190, v221, s[70:71]
	v_add_u32_e32 v190, 0x800, v189
	global_store_dword v190, v222, s[70:71]
	v_add_u32_e32 v190, 0xc00, v189
	global_store_dword v190, v223, s[70:71]
	s_or_b64 exec, exec, s[18:19]
	s_waitcnt vmcnt(48)
	v_pk_add_f32 v[62:63], v[62:63], v[132:133]
	v_pk_add_f32 v[60:61], v[60:61], v[130:131]
	v_pk_add_f32 v[58:59], v[58:59], v[136:137]
	v_pk_add_f32 v[56:57], v[56:57], v[134:135]
	v_pk_add_f32 v[54:55], v[54:55], v[140:141]
	v_pk_add_f32 v[52:53], v[52:53], v[138:139]
	v_pk_add_f32 v[50:51], v[50:51], v[144:145]
	v_pk_add_f32 v[48:49], v[48:49], v[142:143]
	v_add_u32_e32 v191, 0x80000, v187
	v_add_u32_e32 v192, 0x40000, v188
	global_store_dwordx4 v191, v[60:63], s[90:91]
	v_cvt_pk_bf16_f32 v194, v60, v61
	v_cvt_pk_bf16_f32 v195, v62, v63
	global_store_dwordx2 v192, v[194:195], s[72:73]
	v_mul_f32_e32 v185, v61, v61
	v_fmac_f32_e32 v185, v60, v60
	v_mul_f32_e32 v196, v63, v63
	v_fmac_f32_e32 v196, v62, v62
	v_add_f32_e32 v220, v185, v196
	global_store_dwordx4 v191, v[56:59], s[90:91] offset:64
	v_cvt_pk_bf16_f32 v202, v56, v57
	v_cvt_pk_bf16_f32 v203, v58, v59
	global_store_dwordx2 v192, v[202:203], s[72:73] offset:32
	v_mul_f32_e32 v185, v57, v57
	v_fmac_f32_e32 v185, v56, v56
	v_mul_f32_e32 v196, v59, v59
	v_fmac_f32_e32 v196, v58, v58
	v_add_f32_e32 v185, v185, v196
	v_add_f32_e32 v220, v220, v185
	global_store_dwordx4 v191, v[52:55], s[90:91] offset:512
	v_cvt_pk_bf16_f32 v194, v52, v53
	v_cvt_pk_bf16_f32 v195, v54, v55
	global_store_dwordx2 v192, v[194:195], s[72:73] offset:256
	v_mul_f32_e32 v185, v53, v53
	v_fmac_f32_e32 v185, v52, v52
	v_mul_f32_e32 v196, v55, v55
	v_fmac_f32_e32 v196, v54, v54
	v_add_f32_e32 v185, v185, v196
	v_add_f32_e32 v220, v220, v185
	global_store_dwordx4 v191, v[48:51], s[90:91] offset:576
	v_cvt_pk_bf16_f32 v202, v48, v49
	v_cvt_pk_bf16_f32 v203, v50, v51
	global_store_dwordx2 v192, v[202:203], s[72:73] offset:288
	v_mul_f32_e32 v185, v49, v49
	v_fmac_f32_e32 v185, v48, v48
	v_mul_f32_e32 v196, v51, v51
	v_fmac_f32_e32 v196, v50, v50
	v_add_f32_e32 v185, v185, v196
	v_add_f32_e32 v220, v220, v185
	s_waitcnt vmcnt(44)
	v_pk_add_f32 v[46:47], v[46:47], v[148:149]
	v_pk_add_f32 v[44:45], v[44:45], v[146:147]
	v_pk_add_f32 v[42:43], v[42:43], v[152:153]
	v_pk_add_f32 v[40:41], v[40:41], v[150:151]
	v_pk_add_f32 v[38:39], v[38:39], v[156:157]
	v_pk_add_f32 v[36:37], v[36:37], v[154:155]
	v_pk_add_f32 v[34:35], v[34:35], v[160:161]
	v_pk_add_f32 v[32:33], v[32:33], v[158:159]
	v_add_u32_e32 v191, 0x90000, v187
	v_add_u32_e32 v192, 0x48000, v188
	global_store_dwordx4 v191, v[44:47], s[90:91]
	v_cvt_pk_bf16_f32 v194, v44, v45
	v_cvt_pk_bf16_f32 v195, v46, v47
	global_store_dwordx2 v192, v[194:195], s[72:73]
	v_mul_f32_e32 v185, v45, v45
	v_fmac_f32_e32 v185, v44, v44
	v_mul_f32_e32 v196, v47, v47
	v_fmac_f32_e32 v196, v46, v46
	v_add_f32_e32 v221, v185, v196
	global_store_dwordx4 v191, v[40:43], s[90:91] offset:64
	v_cvt_pk_bf16_f32 v202, v40, v41
	v_cvt_pk_bf16_f32 v203, v42, v43
	global_store_dwordx2 v192, v[202:203], s[72:73] offset:32
	v_mul_f32_e32 v185, v41, v41
	v_fmac_f32_e32 v185, v40, v40
	v_mul_f32_e32 v196, v43, v43
	v_fmac_f32_e32 v196, v42, v42
	v_add_f32_e32 v185, v185, v196
	v_add_f32_e32 v221, v221, v185
	global_store_dwordx4 v191, v[36:39], s[90:91] offset:512
	v_cvt_pk_bf16_f32 v194, v36, v37
	v_cvt_pk_bf16_f32 v195, v38, v39
	global_store_dwordx2 v192, v[194:195], s[72:73] offset:256
	v_mul_f32_e32 v185, v37, v37
	v_fmac_f32_e32 v185, v36, v36
	v_mul_f32_e32 v196, v39, v39
	v_fmac_f32_e32 v196, v38, v38
	v_add_f32_e32 v185, v185, v196
	v_add_f32_e32 v221, v221, v185
	global_store_dwordx4 v191, v[32:35], s[90:91] offset:576
	v_cvt_pk_bf16_f32 v202, v32, v33
	v_cvt_pk_bf16_f32 v203, v34, v35
	global_store_dwordx2 v192, v[202:203], s[72:73] offset:288
	v_mul_f32_e32 v185, v33, v33
	v_fmac_f32_e32 v185, v32, v32
	v_mul_f32_e32 v196, v35, v35
	v_fmac_f32_e32 v196, v34, v34
	v_add_f32_e32 v185, v185, v196
	v_add_f32_e32 v221, v221, v185
	s_waitcnt vmcnt(40)
; DI unsigned pk2(float lo, float hi) { f32x2 v = {lo, hi}; hbf2 r = __builtin_convertvector(v, hbf2); return __builtin_bit_cast(unsigned, r); }
;     DI void operator()(f32x4 (&acc)[2][2][4][2], const Unit& u, int wr, int wc, int fr, int fq, LAS unsigned char* lds) const {
;     ...
; #pragma unroll
;             for (int m = 0; m < 4; ++m) {
;                 const int row = row0 + ai * 128 + m * 16;
;                 float* xo = X + (size_t)row * DM + col0; bf16_t* xb = XB + (size_t)row * DM + col0;
;                 float ssq = 0.f;
; #pragma unroll
;                 for (int bj = 0; bj < 2; ++bj)
; #pragma unroll
;                     for (int n = 0; n < 2; ++n) {
;                         const int c = bj * 128 + n * 16;
;                         const f32x4 o = xv[m][bj][n] + acc[ai][bj][m][n] * scale;
;                         *(f32x4*)(xo + c) = o;
;                         if (wxb) { u32x2 w; w.x = pk2(o[0], o[1]); w.y = pk2(o[2], o[3]); *(u32x2*)(xb + c) = w; }
;                         ssq += (o[0] * o[0] + o[1] * o[1]) + (o[2] * o[2] + o[3] * o[3]);
;                     }
;                 ssq += __shfl_xor(ssq, 16); ssq += __shfl_xor(ssq, 32);
;                 if (fq == 0) SS[(size_t)row * 16 + u.pn * 4 + wc] = ssq;
;             }
	v_pk_add_f32 v[30:31], v[30:31], v[164:165]
	v_pk_add_f32 v[28:29], v[28:29], v[162:163]
	v_pk_add_f32 v[26:27], v[26:27], v[168:169]
	v_pk_add_f32 v[24:25], v[24:25], v[166:167]
	v_pk_add_f32 v[22:23], v[22:23], v[172:173]
	v_pk_add_f32 v[20:21], v[20:21], v[170:171]
	v_pk_add_f32 v[18:19], v[18:19], v[176:177]
	v_pk_add_f32 v[16:17], v[16:17], v[174:175]
	v_add_u32_e32 v191, 0xa0000, v187
	v_add_u32_e32 v192, 0x50000, v188
	global_store_dwordx4 v191, v[28:31], s[90:91]
	v_cvt_pk_bf16_f32 v194, v28, v29
	v_cvt_pk_bf16_f32 v195, v30, v31
	global_store_dwordx2 v192, v[194:195], s[72:73]
	v_mul_f32_e32 v185, v29, v29
	v_fmac_f32_e32 v185, v28, v28
	v_mul_f32_e32 v196, v31, v31
	v_fmac_f32_e32 v196, v30, v30
	v_add_f32_e32 v222, v185, v196
	global_store_dwordx4 v191, v[24:27], s[90:91] offset:64
	v_cvt_pk_bf16_f32 v202, v24, v25
	v_cvt_pk_bf16_f32 v203, v26, v27
	global_store_dwordx2 v192, v[202:203], s[72:73] offset:32
	v_mul_f32_e32 v185, v25, v25
	v_fmac_f32_e32 v185, v24, v24
	v_mul_f32_e32 v196, v27, v27
	v_fmac_f32_e32 v196, v26, v26
	v_add_f32_e32 v185, v185, v196
	v_add_f32_e32 v222, v222, v185
	global_store_dwordx4 v191, v[20:23], s[90:91] offset:512
	v_cvt_pk_bf16_f32 v194, v20, v21
	v_cvt_pk_bf16_f32 v195, v22, v23
	global_store_dwordx2 v192, v[194:195], s[72:73] offset:256
	v_mul_f32_e32 v185, v21, v21
	v_fmac_f32_e32 v185, v20, v20
	v_mul_f32_e32 v196, v23, v23
	v_fmac_f32_e32 v196, v22, v22
	v_add_f32_e32 v185, v185, v196
	v_add_f32_e32 v222, v222, v185
	global_store_dwordx4 v191, v[16:19], s[90:91] offset:576
	v_cvt_pk_bf16_f32 v202, v16, v17
	v_cvt_pk_bf16_f32 v203, v18, v19
	global_store_dwordx2 v192, v[202:203], s[72:73] offset:288
	v_mul_f32_e32 v185, v17, v17
	v_fmac_f32_e32 v185, v16, v16
	v_mul_f32_e32 v196, v19, v19
	v_fmac_f32_e32 v196, v18, v18
	v_add_f32_e32 v185, v185, v196
	v_add_f32_e32 v222, v222, v185
	s_waitcnt vmcnt(36)
	v_pk_add_f32 v[14:15], v[14:15], v[206:207]
	v_pk_add_f32 v[12:13], v[12:13], v[204:205]
	v_pk_add_f32 v[10:11], v[10:11], v[210:211]
	v_pk_add_f32 v[8:9], v[8:9], v[208:209]
	v_pk_add_f32 v[6:7], v[6:7], v[214:215]
	v_pk_add_f32 v[4:5], v[4:5], v[212:213]
	v_pk_add_f32 v[2:3], v[2:3], v[218:219]
	v_pk_add_f32 v[0:1], v[0:1], v[216:217]
	v_add_u32_e32 v191, 0xb0000, v187
	v_add_u32_e32 v192, 0x58000, v188
	global_store_dwordx4 v191, v[12:15], s[90:91]
	v_cvt_pk_bf16_f32 v194, v12, v13
	v_cvt_pk_bf16_f32 v195, v14, v15
	global_store_dwordx2 v192, v[194:195], s[72:73]
	v_mul_f32_e32 v185, v13, v13
	v_fmac_f32_e32 v185, v12, v12
	v_mul_f32_e32 v196, v15, v15
	v_fmac_f32_e32 v196, v14, v14
	v_add_f32_e32 v223, v185, v196
	global_store_dwordx4 v191, v[8:11], s[90:91] offset:64
	v_cvt_pk_bf16_f32 v202, v8, v9
	v_cvt_pk_bf16_f32 v203, v10, v11
	global_store_dwordx2 v192, v[202:203], s[72:73] offset:32
	v_mul_f32_e32 v185, v9, v9
	v_fmac_f32_e32 v185, v8, v8
	v_mul_f32_e32 v196, v11, v11
	v_fmac_f32_e32 v196, v10, v10
	v_add_f32_e32 v185, v185, v196
	v_add_f32_e32 v223, v223, v185
	global_store_dwordx4 v191, v[4:7], s[90:91] offset:512
	v_cvt_pk_bf16_f32 v194, v4, v5
	v_cvt_pk_bf16_f32 v195, v6, v7
	global_store_dwordx2 v192, v[194:195], s[72:73] offset:256
	v_mul_f32_e32 v185, v5, v5
	v_fmac_f32_e32 v185, v4, v4
	v_mul_f32_e32 v196, v7, v7
	v_fmac_f32_e32 v196, v6, v6
	v_add_f32_e32 v185, v185, v196
	v_add_f32_e32 v223, v223, v185
	global_store_dwordx4 v191, v[0:3], s[90:91] offset:576
	v_cvt_pk_bf16_f32 v202, v0, v1
	v_cvt_pk_bf16_f32 v203, v2, v3
	global_store_dwordx2 v192, v[202:203], s[72:73] offset:288
	v_mul_f32_e32 v185, v1, v1
	v_fmac_f32_e32 v185, v0, v0
	v_mul_f32_e32 v196, v3, v3
	v_fmac_f32_e32 v196, v2, v2
	v_add_f32_e32 v185, v185, v196
	v_add_f32_e32 v223, v223, v185
	ds_bpermute_b32 v224, v193, v220
	ds_bpermute_b32 v225, v193, v221
	ds_bpermute_b32 v226, v193, v222
	ds_bpermute_b32 v227, v193, v223
	s_waitcnt lgkmcnt(0)
	v_add_f32_e32 v220, v220, v224
	v_add_f32_e32 v221, v221, v225
	v_add_f32_e32 v222, v222, v226
	v_add_f32_e32 v223, v223, v227
	ds_bpermute_b32 v224, v201, v220
	ds_bpermute_b32 v225, v201, v221
	ds_bpermute_b32 v226, v201, v222
	ds_bpermute_b32 v227, v201, v223
	s_waitcnt lgkmcnt(0)
	v_add_f32_e32 v220, v220, v224
	v_add_f32_e32 v221, v221, v225
	v_add_f32_e32 v222, v222, v226
	v_add_f32_e32 v223, v223, v227
	s_and_saveexec_b64 s[18:19], s[38:39]
	v_add_u32_e32 v190, 0x2000, v189
	global_store_dword v190, v220, s[70:71]
	v_add_u32_e32 v190, 0x2400, v189
	global_store_dword v190, v221, s[70:71]
	v_add_u32_e32 v190, 0x2800, v189
	global_store_dword v190, v222, s[70:71]
	v_add_u32_e32 v190, 0x2c00, v189
	global_store_dword v190, v223, s[70:71]
	s_or_b64 exec, exec, s[18:19]
	s_branch .LBB0_1678
